# phase-prologue rstd table: loads of up to 7 units issued back to back, one wait (was one memory round trip per unit)
# speedup vs baseline: 1.0189x; 1.0087x over previous
.LBB0_109:
	s_mov_b32 s99, 0
	v_cmp_gt_i64_e32 vcc, s[10:11], v[10:11]
	s_cbranch_vccnz .Lrt0_w
	s_ashr_i32 s27, s10, 31
	s_lshr_b32 s27, s27, 29
	s_add_i32 s27, s10, s27
	s_ashr_i32 s33, s27, 3
	s_and_b32 s27, s27, -8
	s_sub_i32 s27, s10, s27
	s_cmp_lt_i32 s27, 0
	s_cselect_b32 s52, s24, 0x160
	s_mul_i32 s27, s27, s52
	s_add_i32 s27, s27, s33
	s_mul_hi_i32 s33, s27, 0x2e8ba2e9
	s_lshr_b32 s52, s33, 31
	s_ashr_i32 s33, s33, 4
	s_add_i32 s33, s33, s52
	s_lshl_b32 s52, s33, 2
	s_sub_i32 s53, 0x80, s52
	s_min_i32 s53, s53, 4
	s_mulk_i32 s33, 0x58
	s_sub_i32 s27, s27, s33
	s_and_b32 s27, s27, 3
	s_add_i32 s52, s52, s27
	v_lshl_add_u32 v232, s52, 8, v16
	v_ashrrev_i32_e32 v233, 31, v232
	v_lshlrev_b64 v[232:233], 6, v[232:233]
	v_lshl_add_u64 v[232:233], v[8:9], 0, v[232:233]
	global_load_dwordx4 v[176:179], v[232:233], off
	global_load_dwordx4 v[180:183], v[232:233], off offset:16
	s_add_u32 s10, s10, s22
	s_addc_u32 s11, s11, s21
	s_add_i32 s99, s99, 1
	v_cmp_gt_i64_e32 vcc, s[10:11], v[10:11]
	s_cbranch_vccnz .Lrt0_w
	s_ashr_i32 s27, s10, 31
	s_lshr_b32 s27, s27, 29
	s_add_i32 s27, s10, s27
	s_ashr_i32 s33, s27, 3
	s_and_b32 s27, s27, -8
	s_sub_i32 s27, s10, s27
	s_cmp_lt_i32 s27, 0
	s_cselect_b32 s52, s24, 0x160
	s_mul_i32 s27, s27, s52
	s_add_i32 s27, s27, s33
	s_mul_hi_i32 s33, s27, 0x2e8ba2e9
	s_lshr_b32 s52, s33, 31
	s_ashr_i32 s33, s33, 4
	s_add_i32 s33, s33, s52
	s_lshl_b32 s52, s33, 2
	s_sub_i32 s53, 0x80, s52
	s_min_i32 s53, s53, 4
	s_mulk_i32 s33, 0x58
	s_sub_i32 s27, s27, s33
	s_and_b32 s27, s27, 3
	s_add_i32 s52, s52, s27
	v_lshl_add_u32 v232, s52, 8, v16
	v_ashrrev_i32_e32 v233, 31, v232
	v_lshlrev_b64 v[232:233], 6, v[232:233]
	v_lshl_add_u64 v[232:233], v[8:9], 0, v[232:233]
	global_load_dwordx4 v[184:187], v[232:233], off
	global_load_dwordx4 v[188:191], v[232:233], off offset:16
	s_add_u32 s10, s10, s22
	s_addc_u32 s11, s11, s21
	s_add_i32 s99, s99, 1
	v_cmp_gt_i64_e32 vcc, s[10:11], v[10:11]
	s_cbranch_vccnz .Lrt0_w
	s_ashr_i32 s27, s10, 31
	s_lshr_b32 s27, s27, 29
	s_add_i32 s27, s10, s27
	s_ashr_i32 s33, s27, 3
	s_and_b32 s27, s27, -8
	s_sub_i32 s27, s10, s27
	s_cmp_lt_i32 s27, 0
	s_cselect_b32 s52, s24, 0x160
	s_mul_i32 s27, s27, s52
	s_add_i32 s27, s27, s33
	s_mul_hi_i32 s33, s27, 0x2e8ba2e9
	s_lshr_b32 s52, s33, 31
	s_ashr_i32 s33, s33, 4
	s_add_i32 s33, s33, s52
	s_lshl_b32 s52, s33, 2
	s_sub_i32 s53, 0x80, s52
	s_min_i32 s53, s53, 4
	s_mulk_i32 s33, 0x58
	s_sub_i32 s27, s27, s33
	s_and_b32 s27, s27, 3
	s_add_i32 s52, s52, s27
	v_lshl_add_u32 v232, s52, 8, v16
	v_ashrrev_i32_e32 v233, 31, v232
	v_lshlrev_b64 v[232:233], 6, v[232:233]
	v_lshl_add_u64 v[232:233], v[8:9], 0, v[232:233]
	global_load_dwordx4 v[192:195], v[232:233], off
	global_load_dwordx4 v[196:199], v[232:233], off offset:16
	s_add_u32 s10, s10, s22
	s_addc_u32 s11, s11, s21
	s_add_i32 s99, s99, 1
	v_cmp_gt_i64_e32 vcc, s[10:11], v[10:11]
	s_cbranch_vccnz .Lrt0_w
	s_ashr_i32 s27, s10, 31
	s_lshr_b32 s27, s27, 29
	s_add_i32 s27, s10, s27
	s_ashr_i32 s33, s27, 3
	s_and_b32 s27, s27, -8
	s_sub_i32 s27, s10, s27
	s_cmp_lt_i32 s27, 0
	s_cselect_b32 s52, s24, 0x160
	s_mul_i32 s27, s27, s52
	s_add_i32 s27, s27, s33
	s_mul_hi_i32 s33, s27, 0x2e8ba2e9
	s_lshr_b32 s52, s33, 31
	s_ashr_i32 s33, s33, 4
	s_add_i32 s33, s33, s52
	s_lshl_b32 s52, s33, 2
	s_sub_i32 s53, 0x80, s52
	s_min_i32 s53, s53, 4
	s_mulk_i32 s33, 0x58
	s_sub_i32 s27, s27, s33
	s_and_b32 s27, s27, 3
	s_add_i32 s52, s52, s27
	v_lshl_add_u32 v232, s52, 8, v16
	v_ashrrev_i32_e32 v233, 31, v232
	v_lshlrev_b64 v[232:233], 6, v[232:233]
	v_lshl_add_u64 v[232:233], v[8:9], 0, v[232:233]
	global_load_dwordx4 v[200:203], v[232:233], off
	global_load_dwordx4 v[204:207], v[232:233], off offset:16
	s_add_u32 s10, s10, s22
	s_addc_u32 s11, s11, s21
	s_add_i32 s99, s99, 1
	v_cmp_gt_i64_e32 vcc, s[10:11], v[10:11]
	s_cbranch_vccnz .Lrt0_w
	s_ashr_i32 s27, s10, 31
	s_lshr_b32 s27, s27, 29
	s_add_i32 s27, s10, s27
	s_ashr_i32 s33, s27, 3
	s_and_b32 s27, s27, -8
	s_sub_i32 s27, s10, s27
	s_cmp_lt_i32 s27, 0
	s_cselect_b32 s52, s24, 0x160
	s_mul_i32 s27, s27, s52
	s_add_i32 s27, s27, s33
	s_mul_hi_i32 s33, s27, 0x2e8ba2e9
	s_lshr_b32 s52, s33, 31
	s_ashr_i32 s33, s33, 4
	s_add_i32 s33, s33, s52
	s_lshl_b32 s52, s33, 2
	s_sub_i32 s53, 0x80, s52
	s_min_i32 s53, s53, 4
	s_mulk_i32 s33, 0x58
	s_sub_i32 s27, s27, s33
	s_and_b32 s27, s27, 3
	s_add_i32 s52, s52, s27
	v_lshl_add_u32 v232, s52, 8, v16
	v_ashrrev_i32_e32 v233, 31, v232
	v_lshlrev_b64 v[232:233], 6, v[232:233]
	v_lshl_add_u64 v[232:233], v[8:9], 0, v[232:233]
	global_load_dwordx4 v[208:211], v[232:233], off
	global_load_dwordx4 v[212:215], v[232:233], off offset:16
	s_add_u32 s10, s10, s22
	s_addc_u32 s11, s11, s21
	s_add_i32 s99, s99, 1
	v_cmp_gt_i64_e32 vcc, s[10:11], v[10:11]
	s_cbranch_vccnz .Lrt0_w
	s_ashr_i32 s27, s10, 31
	s_lshr_b32 s27, s27, 29
	s_add_i32 s27, s10, s27
	s_ashr_i32 s33, s27, 3
	s_and_b32 s27, s27, -8
	s_sub_i32 s27, s10, s27
	s_cmp_lt_i32 s27, 0
	s_cselect_b32 s52, s24, 0x160
	s_mul_i32 s27, s27, s52
	s_add_i32 s27, s27, s33
	s_mul_hi_i32 s33, s27, 0x2e8ba2e9
	s_lshr_b32 s52, s33, 31
	s_ashr_i32 s33, s33, 4
	s_add_i32 s33, s33, s52
	s_lshl_b32 s52, s33, 2
	s_sub_i32 s53, 0x80, s52
	s_min_i32 s53, s53, 4
	s_mulk_i32 s33, 0x58
	s_sub_i32 s27, s27, s33
	s_and_b32 s27, s27, 3
	s_add_i32 s52, s52, s27
	v_lshl_add_u32 v232, s52, 8, v16
	v_ashrrev_i32_e32 v233, 31, v232
	v_lshlrev_b64 v[232:233], 6, v[232:233]
	v_lshl_add_u64 v[232:233], v[8:9], 0, v[232:233]
	global_load_dwordx4 v[216:219], v[232:233], off
	global_load_dwordx4 v[220:223], v[232:233], off offset:16
	s_add_u32 s10, s10, s22
	s_addc_u32 s11, s11, s21
	s_add_i32 s99, s99, 1
	v_cmp_gt_i64_e32 vcc, s[10:11], v[10:11]
	s_cbranch_vccnz .Lrt0_w
	s_ashr_i32 s27, s10, 31
	s_lshr_b32 s27, s27, 29
	s_add_i32 s27, s10, s27
	s_ashr_i32 s33, s27, 3
	s_and_b32 s27, s27, -8
	s_sub_i32 s27, s10, s27
	s_cmp_lt_i32 s27, 0
	s_cselect_b32 s52, s24, 0x160
	s_mul_i32 s27, s27, s52
	s_add_i32 s27, s27, s33
	s_mul_hi_i32 s33, s27, 0x2e8ba2e9
	s_lshr_b32 s52, s33, 31
	s_ashr_i32 s33, s33, 4
	s_add_i32 s33, s33, s52
	s_lshl_b32 s52, s33, 2
	s_sub_i32 s53, 0x80, s52
	s_min_i32 s53, s53, 4
	s_mulk_i32 s33, 0x58
	s_sub_i32 s27, s27, s33
	s_and_b32 s27, s27, 3
	s_add_i32 s52, s52, s27
	v_lshl_add_u32 v232, s52, 8, v16
	v_ashrrev_i32_e32 v233, 31, v232
	v_lshlrev_b64 v[232:233], 6, v[232:233]
	v_lshl_add_u64 v[232:233], v[8:9], 0, v[232:233]
	global_load_dwordx4 v[224:227], v[232:233], off
	global_load_dwordx4 v[228:231], v[232:233], off offset:16
	s_add_u32 s10, s10, s22
	s_addc_u32 s11, s11, s21
	s_add_i32 s99, s99, 1
.Lrt0_w:
	s_waitcnt vmcnt(0) lgkmcnt(0)
	s_cmp_gt_u32 s99, 0
	s_cbranch_scc0 .Lrt0_d
	v_add_f32_e32 v176, v176, v177
	v_add_f32_e32 v177, v178, v179
	v_add_f32_e32 v178, v180, v181
	v_add_f32_e32 v179, v182, v183
	v_add_f32_e32 v176, v176, v177
	v_add_f32_e32 v177, v178, v179
	v_add_f32_e32 v176, v176, v177
	s_nop 1
	v_mov_b32_dpp v177, v176 quad_perm:[1,0,3,2] row_mask:0xf bank_mask:0xf
	s_and_saveexec_b64 s[52:53], s[6:7]
	v_add_f32_e32 v176, v176, v177
	v_fmamk_f32 v176, v176, 0x3a800000, v18
	v_rsq_f32_e32 v176, v176
	v_add_u32_e32 v177, s26, v17
	ds_write_b32 v177, v176 offset:14336
	s_or_b64 exec, exec, s[52:53]
	s_cmp_gt_u32 s99, 1
	s_cbranch_scc0 .Lrt0_d
	v_add_f32_e32 v184, v184, v185
	v_add_f32_e32 v185, v186, v187
	v_add_f32_e32 v186, v188, v189
	v_add_f32_e32 v187, v190, v191
	v_add_f32_e32 v184, v184, v185
	v_add_f32_e32 v185, v186, v187
	v_add_f32_e32 v184, v184, v185
	s_nop 1
	v_mov_b32_dpp v185, v184 quad_perm:[1,0,3,2] row_mask:0xf bank_mask:0xf
	s_and_saveexec_b64 s[52:53], s[6:7]
	v_add_f32_e32 v184, v184, v185
	v_fmamk_f32 v184, v184, 0x3a800000, v18
	v_rsq_f32_e32 v184, v184
	v_add_u32_e32 v185, s26, v17
	ds_write_b32 v185, v184 offset:15360
	s_or_b64 exec, exec, s[52:53]
	s_cmp_gt_u32 s99, 2
	s_cbranch_scc0 .Lrt0_d
	v_add_f32_e32 v192, v192, v193
	v_add_f32_e32 v193, v194, v195
	v_add_f32_e32 v194, v196, v197
	v_add_f32_e32 v195, v198, v199
	v_add_f32_e32 v192, v192, v193
	v_add_f32_e32 v193, v194, v195
	v_add_f32_e32 v192, v192, v193
	s_nop 1
	v_mov_b32_dpp v193, v192 quad_perm:[1,0,3,2] row_mask:0xf bank_mask:0xf
	s_and_saveexec_b64 s[52:53], s[6:7]
	v_add_f32_e32 v192, v192, v193
	v_fmamk_f32 v192, v192, 0x3a800000, v18
	v_rsq_f32_e32 v192, v192
	v_add_u32_e32 v193, s26, v17
	ds_write_b32 v193, v192 offset:16384
	s_or_b64 exec, exec, s[52:53]
	s_cmp_gt_u32 s99, 3
	s_cbranch_scc0 .Lrt0_d
	v_add_f32_e32 v200, v200, v201
	v_add_f32_e32 v201, v202, v203
	v_add_f32_e32 v202, v204, v205
	v_add_f32_e32 v203, v206, v207
	v_add_f32_e32 v200, v200, v201
	v_add_f32_e32 v201, v202, v203
	v_add_f32_e32 v200, v200, v201
	s_nop 1
	v_mov_b32_dpp v201, v200 quad_perm:[1,0,3,2] row_mask:0xf bank_mask:0xf
	s_and_saveexec_b64 s[52:53], s[6:7]
	v_add_f32_e32 v200, v200, v201
	v_fmamk_f32 v200, v200, 0x3a800000, v18
	v_rsq_f32_e32 v200, v200
	v_add_u32_e32 v201, s26, v17
	ds_write_b32 v201, v200 offset:17408
	s_or_b64 exec, exec, s[52:53]
	s_cmp_gt_u32 s99, 4
	s_cbranch_scc0 .Lrt0_d
	v_add_f32_e32 v208, v208, v209
	v_add_f32_e32 v209, v210, v211
	v_add_f32_e32 v210, v212, v213
	v_add_f32_e32 v211, v214, v215
	v_add_f32_e32 v208, v208, v209
	v_add_f32_e32 v209, v210, v211
	v_add_f32_e32 v208, v208, v209
	s_nop 1
	v_mov_b32_dpp v209, v208 quad_perm:[1,0,3,2] row_mask:0xf bank_mask:0xf
	s_and_saveexec_b64 s[52:53], s[6:7]
	v_add_f32_e32 v208, v208, v209
	v_fmamk_f32 v208, v208, 0x3a800000, v18
	v_rsq_f32_e32 v208, v208
	v_add_u32_e32 v209, s26, v17
	ds_write_b32 v209, v208 offset:18432
	s_or_b64 exec, exec, s[52:53]
	s_cmp_gt_u32 s99, 5
	s_cbranch_scc0 .Lrt0_d
	v_add_f32_e32 v216, v216, v217
	v_add_f32_e32 v217, v218, v219
	v_add_f32_e32 v218, v220, v221
	v_add_f32_e32 v219, v222, v223
	v_add_f32_e32 v216, v216, v217
	v_add_f32_e32 v217, v218, v219
	v_add_f32_e32 v216, v216, v217
	s_nop 1
	v_mov_b32_dpp v217, v216 quad_perm:[1,0,3,2] row_mask:0xf bank_mask:0xf
	s_and_saveexec_b64 s[52:53], s[6:7]
	v_add_f32_e32 v216, v216, v217
	v_fmamk_f32 v216, v216, 0x3a800000, v18
	v_rsq_f32_e32 v216, v216
	v_add_u32_e32 v217, s26, v17
	ds_write_b32 v217, v216 offset:19456
	s_or_b64 exec, exec, s[52:53]
	s_cmp_gt_u32 s99, 6
	s_cbranch_scc0 .Lrt0_d
	v_add_f32_e32 v224, v224, v225
	v_add_f32_e32 v225, v226, v227
	v_add_f32_e32 v226, v228, v229
	v_add_f32_e32 v227, v230, v231
	v_add_f32_e32 v224, v224, v225
	v_add_f32_e32 v225, v226, v227
	v_add_f32_e32 v224, v224, v225
	s_nop 1
	v_mov_b32_dpp v225, v224 quad_perm:[1,0,3,2] row_mask:0xf bank_mask:0xf
	s_and_saveexec_b64 s[52:53], s[6:7]
	v_add_f32_e32 v224, v224, v225
	v_fmamk_f32 v224, v224, 0x3a800000, v18
	v_rsq_f32_e32 v224, v224
	v_add_u32_e32 v225, s26, v17
	ds_write_b32 v225, v224 offset:20480
	s_or_b64 exec, exec, s[52:53]
.Lrt0_d:
	s_addk_i32 s26, 0x1c00
	s_cmp_lg_u32 s99, 7
	s_cbranch_scc1 .LBB0_112
	s_cmp_lg_u32 s26, 0
	s_cbranch_scc1 .LBB0_109

.LBB0_418:
	s_mov_b32 s99, 0
	v_cmp_gt_i64_e32 vcc, s[10:11], v[10:11]
	s_cbranch_vccnz .Lrt1_w
	s_ashr_i32 s17, s10, 31
	s_lshr_b32 s17, s17, 29
	s_add_i32 s17, s10, s17
	s_ashr_i32 s18, s17, 3
	s_and_b32 s17, s17, -8
	s_sub_i32 s17, s10, s17
	s_cmp_lt_i32 s17, 0
	s_movk_i32 s19, 0xa1
	s_cselect_b32 s19, s19, 0xa0
	s_mul_i32 s17, s17, s19
	s_add_i32 s17, s17, s18
	s_mul_hi_i32 s18, s17, 0x66666667
	s_lshr_b32 s19, s18, 31
	s_ashr_i32 s18, s18, 4
	s_add_i32 s18, s18, s19
	s_lshl_b32 s19, s18, 2
	s_sub_i32 s20, 0x80, s19
	s_min_i32 s20, s20, 4
	s_mul_i32 s18, s18, 40
	s_sub_i32 s17, s17, s18
	s_and_b32 s17, s17, 3
	s_add_i32 s19, s19, s17
	v_lshl_add_u32 v232, s19, 8, v16
	v_ashrrev_i32_e32 v233, 31, v232
	v_lshlrev_b64 v[232:233], 6, v[232:233]
	v_lshl_add_u64 v[232:233], v[8:9], 0, v[232:233]
	global_load_dwordx4 v[176:179], v[232:233], off
	global_load_dwordx4 v[180:183], v[232:233], off offset:16
	s_add_u32 s10, s10, s68
	s_addc_u32 s11, s11, s56
	s_add_i32 s99, s99, 1
	v_cmp_gt_i64_e32 vcc, s[10:11], v[10:11]
	s_cbranch_vccnz .Lrt1_w
	s_ashr_i32 s17, s10, 31
	s_lshr_b32 s17, s17, 29
	s_add_i32 s17, s10, s17
	s_ashr_i32 s18, s17, 3
	s_and_b32 s17, s17, -8
	s_sub_i32 s17, s10, s17
	s_cmp_lt_i32 s17, 0
	s_movk_i32 s19, 0xa1
	s_cselect_b32 s19, s19, 0xa0
	s_mul_i32 s17, s17, s19
	s_add_i32 s17, s17, s18
	s_mul_hi_i32 s18, s17, 0x66666667
	s_lshr_b32 s19, s18, 31
	s_ashr_i32 s18, s18, 4
	s_add_i32 s18, s18, s19
	s_lshl_b32 s19, s18, 2
	s_sub_i32 s20, 0x80, s19
	s_min_i32 s20, s20, 4
	s_mul_i32 s18, s18, 40
	s_sub_i32 s17, s17, s18
	s_and_b32 s17, s17, 3
	s_add_i32 s19, s19, s17
	v_lshl_add_u32 v232, s19, 8, v16
	v_ashrrev_i32_e32 v233, 31, v232
	v_lshlrev_b64 v[232:233], 6, v[232:233]
	v_lshl_add_u64 v[232:233], v[8:9], 0, v[232:233]
	global_load_dwordx4 v[184:187], v[232:233], off
	global_load_dwordx4 v[188:191], v[232:233], off offset:16
	s_add_u32 s10, s10, s68
	s_addc_u32 s11, s11, s56
	s_add_i32 s99, s99, 1
	v_cmp_gt_i64_e32 vcc, s[10:11], v[10:11]
	s_cbranch_vccnz .Lrt1_w
	s_ashr_i32 s17, s10, 31
	s_lshr_b32 s17, s17, 29
	s_add_i32 s17, s10, s17
	s_ashr_i32 s18, s17, 3
	s_and_b32 s17, s17, -8
	s_sub_i32 s17, s10, s17
	s_cmp_lt_i32 s17, 0
	s_movk_i32 s19, 0xa1
	s_cselect_b32 s19, s19, 0xa0
	s_mul_i32 s17, s17, s19
	s_add_i32 s17, s17, s18
	s_mul_hi_i32 s18, s17, 0x66666667
	s_lshr_b32 s19, s18, 31
	s_ashr_i32 s18, s18, 4
	s_add_i32 s18, s18, s19
	s_lshl_b32 s19, s18, 2
	s_sub_i32 s20, 0x80, s19
	s_min_i32 s20, s20, 4
	s_mul_i32 s18, s18, 40
	s_sub_i32 s17, s17, s18
	s_and_b32 s17, s17, 3
	s_add_i32 s19, s19, s17
	v_lshl_add_u32 v232, s19, 8, v16
	v_ashrrev_i32_e32 v233, 31, v232
	v_lshlrev_b64 v[232:233], 6, v[232:233]
	v_lshl_add_u64 v[232:233], v[8:9], 0, v[232:233]
	global_load_dwordx4 v[192:195], v[232:233], off
	global_load_dwordx4 v[196:199], v[232:233], off offset:16
	s_add_u32 s10, s10, s68
	s_addc_u32 s11, s11, s56
	s_add_i32 s99, s99, 1
	v_cmp_gt_i64_e32 vcc, s[10:11], v[10:11]
	s_cbranch_vccnz .Lrt1_w
	s_ashr_i32 s17, s10, 31
	s_lshr_b32 s17, s17, 29
	s_add_i32 s17, s10, s17
	s_ashr_i32 s18, s17, 3
	s_and_b32 s17, s17, -8
	s_sub_i32 s17, s10, s17
	s_cmp_lt_i32 s17, 0
	s_movk_i32 s19, 0xa1
	s_cselect_b32 s19, s19, 0xa0
	s_mul_i32 s17, s17, s19
	s_add_i32 s17, s17, s18
	s_mul_hi_i32 s18, s17, 0x66666667
	s_lshr_b32 s19, s18, 31
	s_ashr_i32 s18, s18, 4
	s_add_i32 s18, s18, s19
	s_lshl_b32 s19, s18, 2
	s_sub_i32 s20, 0x80, s19
	s_min_i32 s20, s20, 4
	s_mul_i32 s18, s18, 40
	s_sub_i32 s17, s17, s18
	s_and_b32 s17, s17, 3
	s_add_i32 s19, s19, s17
	v_lshl_add_u32 v232, s19, 8, v16
	v_ashrrev_i32_e32 v233, 31, v232
	v_lshlrev_b64 v[232:233], 6, v[232:233]
	v_lshl_add_u64 v[232:233], v[8:9], 0, v[232:233]
	global_load_dwordx4 v[200:203], v[232:233], off
	global_load_dwordx4 v[204:207], v[232:233], off offset:16
	s_add_u32 s10, s10, s68
	s_addc_u32 s11, s11, s56
	s_add_i32 s99, s99, 1
	v_cmp_gt_i64_e32 vcc, s[10:11], v[10:11]
	s_cbranch_vccnz .Lrt1_w
	s_ashr_i32 s17, s10, 31
	s_lshr_b32 s17, s17, 29
	s_add_i32 s17, s10, s17
	s_ashr_i32 s18, s17, 3
	s_and_b32 s17, s17, -8
	s_sub_i32 s17, s10, s17
	s_cmp_lt_i32 s17, 0
	s_movk_i32 s19, 0xa1
	s_cselect_b32 s19, s19, 0xa0
	s_mul_i32 s17, s17, s19
	s_add_i32 s17, s17, s18
	s_mul_hi_i32 s18, s17, 0x66666667
	s_lshr_b32 s19, s18, 31
	s_ashr_i32 s18, s18, 4
	s_add_i32 s18, s18, s19
	s_lshl_b32 s19, s18, 2
	s_sub_i32 s20, 0x80, s19
	s_min_i32 s20, s20, 4
	s_mul_i32 s18, s18, 40
	s_sub_i32 s17, s17, s18
	s_and_b32 s17, s17, 3
	s_add_i32 s19, s19, s17
	v_lshl_add_u32 v232, s19, 8, v16
	v_ashrrev_i32_e32 v233, 31, v232
	v_lshlrev_b64 v[232:233], 6, v[232:233]
	v_lshl_add_u64 v[232:233], v[8:9], 0, v[232:233]
	global_load_dwordx4 v[208:211], v[232:233], off
	global_load_dwordx4 v[212:215], v[232:233], off offset:16
	s_add_u32 s10, s10, s68
	s_addc_u32 s11, s11, s56
	s_add_i32 s99, s99, 1
	v_cmp_gt_i64_e32 vcc, s[10:11], v[10:11]
	s_cbranch_vccnz .Lrt1_w
	s_ashr_i32 s17, s10, 31
	s_lshr_b32 s17, s17, 29
	s_add_i32 s17, s10, s17
	s_ashr_i32 s18, s17, 3
	s_and_b32 s17, s17, -8
	s_sub_i32 s17, s10, s17
	s_cmp_lt_i32 s17, 0
	s_movk_i32 s19, 0xa1
	s_cselect_b32 s19, s19, 0xa0
	s_mul_i32 s17, s17, s19
	s_add_i32 s17, s17, s18
	s_mul_hi_i32 s18, s17, 0x66666667
	s_lshr_b32 s19, s18, 31
	s_ashr_i32 s18, s18, 4
	s_add_i32 s18, s18, s19
	s_lshl_b32 s19, s18, 2
	s_sub_i32 s20, 0x80, s19
	s_min_i32 s20, s20, 4
	s_mul_i32 s18, s18, 40
	s_sub_i32 s17, s17, s18
	s_and_b32 s17, s17, 3
	s_add_i32 s19, s19, s17
	v_lshl_add_u32 v232, s19, 8, v16
	v_ashrrev_i32_e32 v233, 31, v232
	v_lshlrev_b64 v[232:233], 6, v[232:233]
	v_lshl_add_u64 v[232:233], v[8:9], 0, v[232:233]
	global_load_dwordx4 v[216:219], v[232:233], off
	global_load_dwordx4 v[220:223], v[232:233], off offset:16
	s_add_u32 s10, s10, s68
	s_addc_u32 s11, s11, s56
	s_add_i32 s99, s99, 1
	v_cmp_gt_i64_e32 vcc, s[10:11], v[10:11]
	s_cbranch_vccnz .Lrt1_w
	s_ashr_i32 s17, s10, 31
	s_lshr_b32 s17, s17, 29
	s_add_i32 s17, s10, s17
	s_ashr_i32 s18, s17, 3
	s_and_b32 s17, s17, -8
	s_sub_i32 s17, s10, s17
	s_cmp_lt_i32 s17, 0
	s_movk_i32 s19, 0xa1
	s_cselect_b32 s19, s19, 0xa0
	s_mul_i32 s17, s17, s19
	s_add_i32 s17, s17, s18
	s_mul_hi_i32 s18, s17, 0x66666667
	s_lshr_b32 s19, s18, 31
	s_ashr_i32 s18, s18, 4
	s_add_i32 s18, s18, s19
	s_lshl_b32 s19, s18, 2
	s_sub_i32 s20, 0x80, s19
	s_min_i32 s20, s20, 4
	s_mul_i32 s18, s18, 40
	s_sub_i32 s17, s17, s18
	s_and_b32 s17, s17, 3
	s_add_i32 s19, s19, s17
	v_lshl_add_u32 v232, s19, 8, v16
	v_ashrrev_i32_e32 v233, 31, v232
	v_lshlrev_b64 v[232:233], 6, v[232:233]
	v_lshl_add_u64 v[232:233], v[8:9], 0, v[232:233]
	global_load_dwordx4 v[224:227], v[232:233], off
	global_load_dwordx4 v[228:231], v[232:233], off offset:16
	s_add_u32 s10, s10, s68
	s_addc_u32 s11, s11, s56
	s_add_i32 s99, s99, 1
.Lrt1_w:
	s_waitcnt vmcnt(0) lgkmcnt(0)
	s_cmp_gt_u32 s99, 0
	s_cbranch_scc0 .Lrt1_d
	v_add_f32_e32 v176, v176, v177
	v_add_f32_e32 v177, v178, v179
	v_add_f32_e32 v178, v180, v181
	v_add_f32_e32 v179, v182, v183
	v_add_f32_e32 v176, v176, v177
	v_add_f32_e32 v177, v178, v179
	v_add_f32_e32 v176, v176, v177
	s_nop 1
	v_mov_b32_dpp v177, v176 quad_perm:[1,0,3,2] row_mask:0xf bank_mask:0xf
	s_and_saveexec_b64 s[52:53], s[8:9]
	v_add_f32_e32 v176, v176, v177
	v_fmamk_f32 v176, v176, 0x3a800000, v18
	v_rsq_f32_e32 v176, v176
	v_add_u32_e32 v177, s14, v17
	ds_write_b32 v177, v176 offset:14336
	s_or_b64 exec, exec, s[52:53]
	s_cmp_gt_u32 s99, 1
	s_cbranch_scc0 .Lrt1_d
	v_add_f32_e32 v184, v184, v185
	v_add_f32_e32 v185, v186, v187
	v_add_f32_e32 v186, v188, v189
	v_add_f32_e32 v187, v190, v191
	v_add_f32_e32 v184, v184, v185
	v_add_f32_e32 v185, v186, v187
	v_add_f32_e32 v184, v184, v185
	s_nop 1
	v_mov_b32_dpp v185, v184 quad_perm:[1,0,3,2] row_mask:0xf bank_mask:0xf
	s_and_saveexec_b64 s[52:53], s[8:9]
	v_add_f32_e32 v184, v184, v185
	v_fmamk_f32 v184, v184, 0x3a800000, v18
	v_rsq_f32_e32 v184, v184
	v_add_u32_e32 v185, s14, v17
	ds_write_b32 v185, v184 offset:15360
	s_or_b64 exec, exec, s[52:53]
	s_cmp_gt_u32 s99, 2
	s_cbranch_scc0 .Lrt1_d
	v_add_f32_e32 v192, v192, v193
	v_add_f32_e32 v193, v194, v195
	v_add_f32_e32 v194, v196, v197
	v_add_f32_e32 v195, v198, v199
	v_add_f32_e32 v192, v192, v193
	v_add_f32_e32 v193, v194, v195
	v_add_f32_e32 v192, v192, v193
	s_nop 1
	v_mov_b32_dpp v193, v192 quad_perm:[1,0,3,2] row_mask:0xf bank_mask:0xf
	s_and_saveexec_b64 s[52:53], s[8:9]
	v_add_f32_e32 v192, v192, v193
	v_fmamk_f32 v192, v192, 0x3a800000, v18
	v_rsq_f32_e32 v192, v192
	v_add_u32_e32 v193, s14, v17
	ds_write_b32 v193, v192 offset:16384
	s_or_b64 exec, exec, s[52:53]
	s_cmp_gt_u32 s99, 3
	s_cbranch_scc0 .Lrt1_d
	v_add_f32_e32 v200, v200, v201
	v_add_f32_e32 v201, v202, v203
	v_add_f32_e32 v202, v204, v205
	v_add_f32_e32 v203, v206, v207
	v_add_f32_e32 v200, v200, v201
	v_add_f32_e32 v201, v202, v203
	v_add_f32_e32 v200, v200, v201
	s_nop 1
	v_mov_b32_dpp v201, v200 quad_perm:[1,0,3,2] row_mask:0xf bank_mask:0xf
	s_and_saveexec_b64 s[52:53], s[8:9]
	v_add_f32_e32 v200, v200, v201
	v_fmamk_f32 v200, v200, 0x3a800000, v18
	v_rsq_f32_e32 v200, v200
	v_add_u32_e32 v201, s14, v17
	ds_write_b32 v201, v200 offset:17408
	s_or_b64 exec, exec, s[52:53]
	s_cmp_gt_u32 s99, 4
	s_cbranch_scc0 .Lrt1_d
	v_add_f32_e32 v208, v208, v209
	v_add_f32_e32 v209, v210, v211
	v_add_f32_e32 v210, v212, v213
	v_add_f32_e32 v211, v214, v215
	v_add_f32_e32 v208, v208, v209
	v_add_f32_e32 v209, v210, v211
	v_add_f32_e32 v208, v208, v209
	s_nop 1
	v_mov_b32_dpp v209, v208 quad_perm:[1,0,3,2] row_mask:0xf bank_mask:0xf
	s_and_saveexec_b64 s[52:53], s[8:9]
	v_add_f32_e32 v208, v208, v209
	v_fmamk_f32 v208, v208, 0x3a800000, v18
	v_rsq_f32_e32 v208, v208
	v_add_u32_e32 v209, s14, v17
	ds_write_b32 v209, v208 offset:18432
	s_or_b64 exec, exec, s[52:53]
	s_cmp_gt_u32 s99, 5
	s_cbranch_scc0 .Lrt1_d
	v_add_f32_e32 v216, v216, v217
	v_add_f32_e32 v217, v218, v219
	v_add_f32_e32 v218, v220, v221
	v_add_f32_e32 v219, v222, v223
	v_add_f32_e32 v216, v216, v217
	v_add_f32_e32 v217, v218, v219
	v_add_f32_e32 v216, v216, v217
	s_nop 1
	v_mov_b32_dpp v217, v216 quad_perm:[1,0,3,2] row_mask:0xf bank_mask:0xf
	s_and_saveexec_b64 s[52:53], s[8:9]
	v_add_f32_e32 v216, v216, v217
	v_fmamk_f32 v216, v216, 0x3a800000, v18
	v_rsq_f32_e32 v216, v216
	v_add_u32_e32 v217, s14, v17
	ds_write_b32 v217, v216 offset:19456
	s_or_b64 exec, exec, s[52:53]
	s_cmp_gt_u32 s99, 6
	s_cbranch_scc0 .Lrt1_d
	v_add_f32_e32 v224, v224, v225
	v_add_f32_e32 v225, v226, v227
	v_add_f32_e32 v226, v228, v229
	v_add_f32_e32 v227, v230, v231
	v_add_f32_e32 v224, v224, v225
	v_add_f32_e32 v225, v226, v227
	v_add_f32_e32 v224, v224, v225
	s_nop 1
	v_mov_b32_dpp v225, v224 quad_perm:[1,0,3,2] row_mask:0xf bank_mask:0xf
	s_and_saveexec_b64 s[52:53], s[8:9]
	v_add_f32_e32 v224, v224, v225
	v_fmamk_f32 v224, v224, 0x3a800000, v18
	v_rsq_f32_e32 v224, v224
	v_add_u32_e32 v225, s14, v17
	ds_write_b32 v225, v224 offset:20480
	s_or_b64 exec, exec, s[52:53]
.Lrt1_d:
	s_addk_i32 s14, 0x1c00
	s_cmp_lg_u32 s99, 7
	s_cbranch_scc1 .LBB0_421
	s_cmp_lg_u32 s14, 0
	s_cbranch_scc1 .LBB0_418

.LBB0_1137:
	s_mov_b32 s99, 0
	v_cmp_gt_i64_e32 vcc, s[8:9], v[10:11]
	s_cbranch_vccnz .Lrt2_w
	s_ashr_i32 s10, s8, 31
	s_lshr_b32 s10, s10, 29
	s_add_i32 s10, s8, s10
	s_ashr_i32 s11, s10, 3
	s_and_b32 s10, s10, -8
	s_sub_i32 s10, s8, s10
	s_cmp_lt_i32 s10, 0
	s_cselect_b32 s27, s24, 0x160
	s_mul_i32 s10, s10, s27
	s_add_i32 s10, s10, s11
	s_mul_hi_i32 s11, s10, 0x2e8ba2e9
	s_lshr_b32 s27, s11, 31
	s_ashr_i32 s11, s11, 4
	s_add_i32 s11, s11, s27
	s_lshl_b32 s27, s11, 2
	s_sub_i32 s33, 0x80, s27
	s_min_i32 s33, s33, 4
	s_mulk_i32 s11, 0x58
	s_sub_i32 s10, s10, s11
	s_and_b32 s10, s10, 3
	s_add_i32 s27, s27, s10
	v_lshl_add_u32 v232, s27, 8, v16
	v_ashrrev_i32_e32 v233, 31, v232
	v_lshlrev_b64 v[232:233], 6, v[232:233]
	v_lshl_add_u64 v[232:233], v[8:9], 0, v[232:233]
	global_load_dwordx4 v[176:179], v[232:233], off
	global_load_dwordx4 v[180:183], v[232:233], off offset:16
	s_add_u32 s8, s8, s22
	s_addc_u32 s9, s9, s21
	s_add_i32 s99, s99, 1
	v_cmp_gt_i64_e32 vcc, s[8:9], v[10:11]
	s_cbranch_vccnz .Lrt2_w
	s_ashr_i32 s10, s8, 31
	s_lshr_b32 s10, s10, 29
	s_add_i32 s10, s8, s10
	s_ashr_i32 s11, s10, 3
	s_and_b32 s10, s10, -8
	s_sub_i32 s10, s8, s10
	s_cmp_lt_i32 s10, 0
	s_cselect_b32 s27, s24, 0x160
	s_mul_i32 s10, s10, s27
	s_add_i32 s10, s10, s11
	s_mul_hi_i32 s11, s10, 0x2e8ba2e9
	s_lshr_b32 s27, s11, 31
	s_ashr_i32 s11, s11, 4
	s_add_i32 s11, s11, s27
	s_lshl_b32 s27, s11, 2
	s_sub_i32 s33, 0x80, s27
	s_min_i32 s33, s33, 4
	s_mulk_i32 s11, 0x58
	s_sub_i32 s10, s10, s11
	s_and_b32 s10, s10, 3
	s_add_i32 s27, s27, s10
	v_lshl_add_u32 v232, s27, 8, v16
	v_ashrrev_i32_e32 v233, 31, v232
	v_lshlrev_b64 v[232:233], 6, v[232:233]
	v_lshl_add_u64 v[232:233], v[8:9], 0, v[232:233]
	global_load_dwordx4 v[184:187], v[232:233], off
	global_load_dwordx4 v[188:191], v[232:233], off offset:16
	s_add_u32 s8, s8, s22
	s_addc_u32 s9, s9, s21
	s_add_i32 s99, s99, 1
	v_cmp_gt_i64_e32 vcc, s[8:9], v[10:11]
	s_cbranch_vccnz .Lrt2_w
	s_ashr_i32 s10, s8, 31
	s_lshr_b32 s10, s10, 29
	s_add_i32 s10, s8, s10
	s_ashr_i32 s11, s10, 3
	s_and_b32 s10, s10, -8
	s_sub_i32 s10, s8, s10
	s_cmp_lt_i32 s10, 0
	s_cselect_b32 s27, s24, 0x160
	s_mul_i32 s10, s10, s27
	s_add_i32 s10, s10, s11
	s_mul_hi_i32 s11, s10, 0x2e8ba2e9
	s_lshr_b32 s27, s11, 31
	s_ashr_i32 s11, s11, 4
	s_add_i32 s11, s11, s27
	s_lshl_b32 s27, s11, 2
	s_sub_i32 s33, 0x80, s27
	s_min_i32 s33, s33, 4
	s_mulk_i32 s11, 0x58
	s_sub_i32 s10, s10, s11
	s_and_b32 s10, s10, 3
	s_add_i32 s27, s27, s10
	v_lshl_add_u32 v232, s27, 8, v16
	v_ashrrev_i32_e32 v233, 31, v232
	v_lshlrev_b64 v[232:233], 6, v[232:233]
	v_lshl_add_u64 v[232:233], v[8:9], 0, v[232:233]
	global_load_dwordx4 v[192:195], v[232:233], off
	global_load_dwordx4 v[196:199], v[232:233], off offset:16
	s_add_u32 s8, s8, s22
	s_addc_u32 s9, s9, s21
	s_add_i32 s99, s99, 1
	v_cmp_gt_i64_e32 vcc, s[8:9], v[10:11]
	s_cbranch_vccnz .Lrt2_w
	s_ashr_i32 s10, s8, 31
	s_lshr_b32 s10, s10, 29
	s_add_i32 s10, s8, s10
	s_ashr_i32 s11, s10, 3
	s_and_b32 s10, s10, -8
	s_sub_i32 s10, s8, s10
	s_cmp_lt_i32 s10, 0
	s_cselect_b32 s27, s24, 0x160
	s_mul_i32 s10, s10, s27
	s_add_i32 s10, s10, s11
	s_mul_hi_i32 s11, s10, 0x2e8ba2e9
	s_lshr_b32 s27, s11, 31
	s_ashr_i32 s11, s11, 4
	s_add_i32 s11, s11, s27
	s_lshl_b32 s27, s11, 2
	s_sub_i32 s33, 0x80, s27
	s_min_i32 s33, s33, 4
	s_mulk_i32 s11, 0x58
	s_sub_i32 s10, s10, s11
	s_and_b32 s10, s10, 3
	s_add_i32 s27, s27, s10
	v_lshl_add_u32 v232, s27, 8, v16
	v_ashrrev_i32_e32 v233, 31, v232
	v_lshlrev_b64 v[232:233], 6, v[232:233]
	v_lshl_add_u64 v[232:233], v[8:9], 0, v[232:233]
	global_load_dwordx4 v[200:203], v[232:233], off
	global_load_dwordx4 v[204:207], v[232:233], off offset:16
	s_add_u32 s8, s8, s22
	s_addc_u32 s9, s9, s21
	s_add_i32 s99, s99, 1
	v_cmp_gt_i64_e32 vcc, s[8:9], v[10:11]
	s_cbranch_vccnz .Lrt2_w
	s_ashr_i32 s10, s8, 31
	s_lshr_b32 s10, s10, 29
	s_add_i32 s10, s8, s10
	s_ashr_i32 s11, s10, 3
	s_and_b32 s10, s10, -8
	s_sub_i32 s10, s8, s10
	s_cmp_lt_i32 s10, 0
	s_cselect_b32 s27, s24, 0x160
	s_mul_i32 s10, s10, s27
	s_add_i32 s10, s10, s11
	s_mul_hi_i32 s11, s10, 0x2e8ba2e9
	s_lshr_b32 s27, s11, 31
	s_ashr_i32 s11, s11, 4
	s_add_i32 s11, s11, s27
	s_lshl_b32 s27, s11, 2
	s_sub_i32 s33, 0x80, s27
	s_min_i32 s33, s33, 4
	s_mulk_i32 s11, 0x58
	s_sub_i32 s10, s10, s11
	s_and_b32 s10, s10, 3
	s_add_i32 s27, s27, s10
	v_lshl_add_u32 v232, s27, 8, v16
	v_ashrrev_i32_e32 v233, 31, v232
	v_lshlrev_b64 v[232:233], 6, v[232:233]
	v_lshl_add_u64 v[232:233], v[8:9], 0, v[232:233]
	global_load_dwordx4 v[208:211], v[232:233], off
	global_load_dwordx4 v[212:215], v[232:233], off offset:16
	s_add_u32 s8, s8, s22
	s_addc_u32 s9, s9, s21
	s_add_i32 s99, s99, 1
	v_cmp_gt_i64_e32 vcc, s[8:9], v[10:11]
	s_cbranch_vccnz .Lrt2_w
	s_ashr_i32 s10, s8, 31
	s_lshr_b32 s10, s10, 29
	s_add_i32 s10, s8, s10
	s_ashr_i32 s11, s10, 3
	s_and_b32 s10, s10, -8
	s_sub_i32 s10, s8, s10
	s_cmp_lt_i32 s10, 0
	s_cselect_b32 s27, s24, 0x160
	s_mul_i32 s10, s10, s27
	s_add_i32 s10, s10, s11
	s_mul_hi_i32 s11, s10, 0x2e8ba2e9
	s_lshr_b32 s27, s11, 31
	s_ashr_i32 s11, s11, 4
	s_add_i32 s11, s11, s27
	s_lshl_b32 s27, s11, 2
	s_sub_i32 s33, 0x80, s27
	s_min_i32 s33, s33, 4
	s_mulk_i32 s11, 0x58
	s_sub_i32 s10, s10, s11
	s_and_b32 s10, s10, 3
	s_add_i32 s27, s27, s10
	v_lshl_add_u32 v232, s27, 8, v16
	v_ashrrev_i32_e32 v233, 31, v232
	v_lshlrev_b64 v[232:233], 6, v[232:233]
	v_lshl_add_u64 v[232:233], v[8:9], 0, v[232:233]
	global_load_dwordx4 v[216:219], v[232:233], off
	global_load_dwordx4 v[220:223], v[232:233], off offset:16
	s_add_u32 s8, s8, s22
	s_addc_u32 s9, s9, s21
	s_add_i32 s99, s99, 1
	v_cmp_gt_i64_e32 vcc, s[8:9], v[10:11]
	s_cbranch_vccnz .Lrt2_w
	s_ashr_i32 s10, s8, 31
	s_lshr_b32 s10, s10, 29
	s_add_i32 s10, s8, s10
	s_ashr_i32 s11, s10, 3
	s_and_b32 s10, s10, -8
	s_sub_i32 s10, s8, s10
	s_cmp_lt_i32 s10, 0
	s_cselect_b32 s27, s24, 0x160
	s_mul_i32 s10, s10, s27
	s_add_i32 s10, s10, s11
	s_mul_hi_i32 s11, s10, 0x2e8ba2e9
	s_lshr_b32 s27, s11, 31
	s_ashr_i32 s11, s11, 4
	s_add_i32 s11, s11, s27
	s_lshl_b32 s27, s11, 2
	s_sub_i32 s33, 0x80, s27
	s_min_i32 s33, s33, 4
	s_mulk_i32 s11, 0x58
	s_sub_i32 s10, s10, s11
	s_and_b32 s10, s10, 3
	s_add_i32 s27, s27, s10
	v_lshl_add_u32 v232, s27, 8, v16
	v_ashrrev_i32_e32 v233, 31, v232
	v_lshlrev_b64 v[232:233], 6, v[232:233]
	v_lshl_add_u64 v[232:233], v[8:9], 0, v[232:233]
	global_load_dwordx4 v[224:227], v[232:233], off
	global_load_dwordx4 v[228:231], v[232:233], off offset:16
	s_add_u32 s8, s8, s22
	s_addc_u32 s9, s9, s21
	s_add_i32 s99, s99, 1
.Lrt2_w:
	s_waitcnt vmcnt(0) lgkmcnt(0)
	s_cmp_gt_u32 s99, 0
	s_cbranch_scc0 .Lrt2_d
	v_add_f32_e32 v176, v176, v177
	v_add_f32_e32 v177, v178, v179
	v_add_f32_e32 v178, v180, v181
	v_add_f32_e32 v179, v182, v183
	v_add_f32_e32 v176, v176, v177
	v_add_f32_e32 v177, v178, v179
	v_add_f32_e32 v176, v176, v177
	s_nop 1
	v_mov_b32_dpp v177, v176 quad_perm:[1,0,3,2] row_mask:0xf bank_mask:0xf
	s_and_saveexec_b64 s[10:11], s[4:5]
	v_add_f32_e32 v176, v176, v177
	v_fmamk_f32 v176, v176, 0x3a800000, v18
	v_rsq_f32_e32 v176, v176
	v_add_u32_e32 v177, s26, v17
	ds_write_b32 v177, v176 offset:14336
	s_or_b64 exec, exec, s[10:11]
	s_cmp_gt_u32 s99, 1
	s_cbranch_scc0 .Lrt2_d
	v_add_f32_e32 v184, v184, v185
	v_add_f32_e32 v185, v186, v187
	v_add_f32_e32 v186, v188, v189
	v_add_f32_e32 v187, v190, v191
	v_add_f32_e32 v184, v184, v185
	v_add_f32_e32 v185, v186, v187
	v_add_f32_e32 v184, v184, v185
	s_nop 1
	v_mov_b32_dpp v185, v184 quad_perm:[1,0,3,2] row_mask:0xf bank_mask:0xf
	s_and_saveexec_b64 s[10:11], s[4:5]
	v_add_f32_e32 v184, v184, v185
	v_fmamk_f32 v184, v184, 0x3a800000, v18
	v_rsq_f32_e32 v184, v184
	v_add_u32_e32 v185, s26, v17
	ds_write_b32 v185, v184 offset:15360
	s_or_b64 exec, exec, s[10:11]
	s_cmp_gt_u32 s99, 2
	s_cbranch_scc0 .Lrt2_d
	v_add_f32_e32 v192, v192, v193
	v_add_f32_e32 v193, v194, v195
	v_add_f32_e32 v194, v196, v197
	v_add_f32_e32 v195, v198, v199
	v_add_f32_e32 v192, v192, v193
	v_add_f32_e32 v193, v194, v195
	v_add_f32_e32 v192, v192, v193
	s_nop 1
	v_mov_b32_dpp v193, v192 quad_perm:[1,0,3,2] row_mask:0xf bank_mask:0xf
	s_and_saveexec_b64 s[10:11], s[4:5]
	v_add_f32_e32 v192, v192, v193
	v_fmamk_f32 v192, v192, 0x3a800000, v18
	v_rsq_f32_e32 v192, v192
	v_add_u32_e32 v193, s26, v17
	ds_write_b32 v193, v192 offset:16384
	s_or_b64 exec, exec, s[10:11]
	s_cmp_gt_u32 s99, 3
	s_cbranch_scc0 .Lrt2_d
	v_add_f32_e32 v200, v200, v201
	v_add_f32_e32 v201, v202, v203
	v_add_f32_e32 v202, v204, v205
	v_add_f32_e32 v203, v206, v207
	v_add_f32_e32 v200, v200, v201
	v_add_f32_e32 v201, v202, v203
	v_add_f32_e32 v200, v200, v201
	s_nop 1
	v_mov_b32_dpp v201, v200 quad_perm:[1,0,3,2] row_mask:0xf bank_mask:0xf
	s_and_saveexec_b64 s[10:11], s[4:5]
	v_add_f32_e32 v200, v200, v201
	v_fmamk_f32 v200, v200, 0x3a800000, v18
	v_rsq_f32_e32 v200, v200
	v_add_u32_e32 v201, s26, v17
	ds_write_b32 v201, v200 offset:17408
	s_or_b64 exec, exec, s[10:11]
	s_cmp_gt_u32 s99, 4
	s_cbranch_scc0 .Lrt2_d
	v_add_f32_e32 v208, v208, v209
	v_add_f32_e32 v209, v210, v211
	v_add_f32_e32 v210, v212, v213
	v_add_f32_e32 v211, v214, v215
	v_add_f32_e32 v208, v208, v209
	v_add_f32_e32 v209, v210, v211
	v_add_f32_e32 v208, v208, v209
	s_nop 1
	v_mov_b32_dpp v209, v208 quad_perm:[1,0,3,2] row_mask:0xf bank_mask:0xf
	s_and_saveexec_b64 s[10:11], s[4:5]
	v_add_f32_e32 v208, v208, v209
	v_fmamk_f32 v208, v208, 0x3a800000, v18
	v_rsq_f32_e32 v208, v208
	v_add_u32_e32 v209, s26, v17
	ds_write_b32 v209, v208 offset:18432
	s_or_b64 exec, exec, s[10:11]
	s_cmp_gt_u32 s99, 5
	s_cbranch_scc0 .Lrt2_d
	v_add_f32_e32 v216, v216, v217
	v_add_f32_e32 v217, v218, v219
	v_add_f32_e32 v218, v220, v221
	v_add_f32_e32 v219, v222, v223
	v_add_f32_e32 v216, v216, v217
	v_add_f32_e32 v217, v218, v219
	v_add_f32_e32 v216, v216, v217
	s_nop 1
	v_mov_b32_dpp v217, v216 quad_perm:[1,0,3,2] row_mask:0xf bank_mask:0xf
	s_and_saveexec_b64 s[10:11], s[4:5]
	v_add_f32_e32 v216, v216, v217
	v_fmamk_f32 v216, v216, 0x3a800000, v18
	v_rsq_f32_e32 v216, v216
	v_add_u32_e32 v217, s26, v17
	ds_write_b32 v217, v216 offset:19456
	s_or_b64 exec, exec, s[10:11]
	s_cmp_gt_u32 s99, 6
	s_cbranch_scc0 .Lrt2_d
	v_add_f32_e32 v224, v224, v225
	v_add_f32_e32 v225, v226, v227
	v_add_f32_e32 v226, v228, v229
	v_add_f32_e32 v227, v230, v231
	v_add_f32_e32 v224, v224, v225
	v_add_f32_e32 v225, v226, v227
	v_add_f32_e32 v224, v224, v225
	s_nop 1
	v_mov_b32_dpp v225, v224 quad_perm:[1,0,3,2] row_mask:0xf bank_mask:0xf
	s_and_saveexec_b64 s[10:11], s[4:5]
	v_add_f32_e32 v224, v224, v225
	v_fmamk_f32 v224, v224, 0x3a800000, v18
	v_rsq_f32_e32 v224, v224
	v_add_u32_e32 v225, s26, v17
	ds_write_b32 v225, v224 offset:20480
	s_or_b64 exec, exec, s[10:11]

.LBB0_1749:
	s_mov_b32 s99, 0
	v_cmp_gt_i64_e32 vcc, s[8:9], v[10:11]
	s_cbranch_vccnz .Lrt4_w
	s_ashr_i32 s10, s8, 31
	s_lshr_b32 s10, s10, 29
	s_add_i32 s10, s8, s10
	s_ashr_i32 s11, s10, 3
	s_and_b32 s10, s10, -8
	s_sub_i32 s10, s8, s10
	s_cmp_lt_i32 s10, 0
	s_cselect_b32 s27, s24, 0xc0
	s_mul_i32 s10, s10, s27
	s_add_i32 s10, s10, s11
	s_mul_hi_i32 s11, s10, 0x2aaaaaab
	s_lshr_b32 s27, s11, 31
	s_ashr_i32 s11, s11, 3
	s_add_i32 s11, s11, s27
	s_lshl_b32 s27, s11, 2
	s_sub_i32 s33, 0x80, s27
	s_min_i32 s33, s33, 4
	s_mul_i32 s11, s11, 48
	s_sub_i32 s10, s10, s11
	s_and_b32 s10, s10, 3
	s_add_i32 s27, s27, s10
	v_lshl_add_u32 v232, s27, 8, v16
	v_ashrrev_i32_e32 v233, 31, v232
	v_lshlrev_b64 v[232:233], 6, v[232:233]
	v_lshl_add_u64 v[232:233], v[8:9], 0, v[232:233]
	global_load_dwordx4 v[176:179], v[232:233], off
	global_load_dwordx4 v[180:183], v[232:233], off offset:16
	s_add_u32 s8, s8, s22
	s_addc_u32 s9, s9, s16
	s_add_i32 s99, s99, 1
	v_cmp_gt_i64_e32 vcc, s[8:9], v[10:11]
	s_cbranch_vccnz .Lrt4_w
	s_ashr_i32 s10, s8, 31
	s_lshr_b32 s10, s10, 29
	s_add_i32 s10, s8, s10
	s_ashr_i32 s11, s10, 3
	s_and_b32 s10, s10, -8
	s_sub_i32 s10, s8, s10
	s_cmp_lt_i32 s10, 0
	s_cselect_b32 s27, s24, 0xc0
	s_mul_i32 s10, s10, s27
	s_add_i32 s10, s10, s11
	s_mul_hi_i32 s11, s10, 0x2aaaaaab
	s_lshr_b32 s27, s11, 31
	s_ashr_i32 s11, s11, 3
	s_add_i32 s11, s11, s27
	s_lshl_b32 s27, s11, 2
	s_sub_i32 s33, 0x80, s27
	s_min_i32 s33, s33, 4
	s_mul_i32 s11, s11, 48
	s_sub_i32 s10, s10, s11
	s_and_b32 s10, s10, 3
	s_add_i32 s27, s27, s10
	v_lshl_add_u32 v232, s27, 8, v16
	v_ashrrev_i32_e32 v233, 31, v232
	v_lshlrev_b64 v[232:233], 6, v[232:233]
	v_lshl_add_u64 v[232:233], v[8:9], 0, v[232:233]
	global_load_dwordx4 v[184:187], v[232:233], off
	global_load_dwordx4 v[188:191], v[232:233], off offset:16
	s_add_u32 s8, s8, s22
	s_addc_u32 s9, s9, s16
	s_add_i32 s99, s99, 1
	v_cmp_gt_i64_e32 vcc, s[8:9], v[10:11]
	s_cbranch_vccnz .Lrt4_w
	s_ashr_i32 s10, s8, 31
	s_lshr_b32 s10, s10, 29
	s_add_i32 s10, s8, s10
	s_ashr_i32 s11, s10, 3
	s_and_b32 s10, s10, -8
	s_sub_i32 s10, s8, s10
	s_cmp_lt_i32 s10, 0
	s_cselect_b32 s27, s24, 0xc0
	s_mul_i32 s10, s10, s27
	s_add_i32 s10, s10, s11
	s_mul_hi_i32 s11, s10, 0x2aaaaaab
	s_lshr_b32 s27, s11, 31
	s_ashr_i32 s11, s11, 3
	s_add_i32 s11, s11, s27
	s_lshl_b32 s27, s11, 2
	s_sub_i32 s33, 0x80, s27
	s_min_i32 s33, s33, 4
	s_mul_i32 s11, s11, 48
	s_sub_i32 s10, s10, s11
	s_and_b32 s10, s10, 3
	s_add_i32 s27, s27, s10
	v_lshl_add_u32 v232, s27, 8, v16
	v_ashrrev_i32_e32 v233, 31, v232
	v_lshlrev_b64 v[232:233], 6, v[232:233]
	v_lshl_add_u64 v[232:233], v[8:9], 0, v[232:233]
	global_load_dwordx4 v[192:195], v[232:233], off
	global_load_dwordx4 v[196:199], v[232:233], off offset:16
	s_add_u32 s8, s8, s22
	s_addc_u32 s9, s9, s16
	s_add_i32 s99, s99, 1
	v_cmp_gt_i64_e32 vcc, s[8:9], v[10:11]
	s_cbranch_vccnz .Lrt4_w
	s_ashr_i32 s10, s8, 31
	s_lshr_b32 s10, s10, 29
	s_add_i32 s10, s8, s10
	s_ashr_i32 s11, s10, 3
	s_and_b32 s10, s10, -8
	s_sub_i32 s10, s8, s10
	s_cmp_lt_i32 s10, 0
	s_cselect_b32 s27, s24, 0xc0
	s_mul_i32 s10, s10, s27
	s_add_i32 s10, s10, s11
	s_mul_hi_i32 s11, s10, 0x2aaaaaab
	s_lshr_b32 s27, s11, 31
	s_ashr_i32 s11, s11, 3
	s_add_i32 s11, s11, s27
	s_lshl_b32 s27, s11, 2
	s_sub_i32 s33, 0x80, s27
	s_min_i32 s33, s33, 4
	s_mul_i32 s11, s11, 48
	s_sub_i32 s10, s10, s11
	s_and_b32 s10, s10, 3
	s_add_i32 s27, s27, s10
	v_lshl_add_u32 v232, s27, 8, v16
	v_ashrrev_i32_e32 v233, 31, v232
	v_lshlrev_b64 v[232:233], 6, v[232:233]
	v_lshl_add_u64 v[232:233], v[8:9], 0, v[232:233]
	global_load_dwordx4 v[200:203], v[232:233], off
	global_load_dwordx4 v[204:207], v[232:233], off offset:16
	s_add_u32 s8, s8, s22
	s_addc_u32 s9, s9, s16
	s_add_i32 s99, s99, 1
	v_cmp_gt_i64_e32 vcc, s[8:9], v[10:11]
	s_cbranch_vccnz .Lrt4_w
	s_ashr_i32 s10, s8, 31
	s_lshr_b32 s10, s10, 29
	s_add_i32 s10, s8, s10
	s_ashr_i32 s11, s10, 3
	s_and_b32 s10, s10, -8
	s_sub_i32 s10, s8, s10
	s_cmp_lt_i32 s10, 0
	s_cselect_b32 s27, s24, 0xc0
	s_mul_i32 s10, s10, s27
	s_add_i32 s10, s10, s11
	s_mul_hi_i32 s11, s10, 0x2aaaaaab
	s_lshr_b32 s27, s11, 31
	s_ashr_i32 s11, s11, 3
	s_add_i32 s11, s11, s27
	s_lshl_b32 s27, s11, 2
	s_sub_i32 s33, 0x80, s27
	s_min_i32 s33, s33, 4
	s_mul_i32 s11, s11, 48
	s_sub_i32 s10, s10, s11
	s_and_b32 s10, s10, 3
	s_add_i32 s27, s27, s10
	v_lshl_add_u32 v232, s27, 8, v16
	v_ashrrev_i32_e32 v233, 31, v232
	v_lshlrev_b64 v[232:233], 6, v[232:233]
	v_lshl_add_u64 v[232:233], v[8:9], 0, v[232:233]
	global_load_dwordx4 v[208:211], v[232:233], off
	global_load_dwordx4 v[212:215], v[232:233], off offset:16
	s_add_u32 s8, s8, s22
	s_addc_u32 s9, s9, s16
	s_add_i32 s99, s99, 1
	v_cmp_gt_i64_e32 vcc, s[8:9], v[10:11]
	s_cbranch_vccnz .Lrt4_w
	s_ashr_i32 s10, s8, 31
	s_lshr_b32 s10, s10, 29
	s_add_i32 s10, s8, s10
	s_ashr_i32 s11, s10, 3
	s_and_b32 s10, s10, -8
	s_sub_i32 s10, s8, s10
	s_cmp_lt_i32 s10, 0
	s_cselect_b32 s27, s24, 0xc0
	s_mul_i32 s10, s10, s27
	s_add_i32 s10, s10, s11
	s_mul_hi_i32 s11, s10, 0x2aaaaaab
	s_lshr_b32 s27, s11, 31
	s_ashr_i32 s11, s11, 3
	s_add_i32 s11, s11, s27
	s_lshl_b32 s27, s11, 2
	s_sub_i32 s33, 0x80, s27
	s_min_i32 s33, s33, 4
	s_mul_i32 s11, s11, 48
	s_sub_i32 s10, s10, s11
	s_and_b32 s10, s10, 3
	s_add_i32 s27, s27, s10
	v_lshl_add_u32 v232, s27, 8, v16
	v_ashrrev_i32_e32 v233, 31, v232
	v_lshlrev_b64 v[232:233], 6, v[232:233]
	v_lshl_add_u64 v[232:233], v[8:9], 0, v[232:233]
	global_load_dwordx4 v[216:219], v[232:233], off
	global_load_dwordx4 v[220:223], v[232:233], off offset:16
	s_add_u32 s8, s8, s22
	s_addc_u32 s9, s9, s16
	s_add_i32 s99, s99, 1
	v_cmp_gt_i64_e32 vcc, s[8:9], v[10:11]
	s_cbranch_vccnz .Lrt4_w
	s_ashr_i32 s10, s8, 31
	s_lshr_b32 s10, s10, 29
	s_add_i32 s10, s8, s10
	s_ashr_i32 s11, s10, 3
	s_and_b32 s10, s10, -8
	s_sub_i32 s10, s8, s10
	s_cmp_lt_i32 s10, 0
	s_cselect_b32 s27, s24, 0xc0
	s_mul_i32 s10, s10, s27
	s_add_i32 s10, s10, s11
	s_mul_hi_i32 s11, s10, 0x2aaaaaab
	s_lshr_b32 s27, s11, 31
	s_ashr_i32 s11, s11, 3
	s_add_i32 s11, s11, s27
	s_lshl_b32 s27, s11, 2
	s_sub_i32 s33, 0x80, s27
	s_min_i32 s33, s33, 4
	s_mul_i32 s11, s11, 48
	s_sub_i32 s10, s10, s11
	s_and_b32 s10, s10, 3
	s_add_i32 s27, s27, s10
	v_lshl_add_u32 v232, s27, 8, v16
	v_ashrrev_i32_e32 v233, 31, v232
	v_lshlrev_b64 v[232:233], 6, v[232:233]
	v_lshl_add_u64 v[232:233], v[8:9], 0, v[232:233]
	global_load_dwordx4 v[224:227], v[232:233], off
	global_load_dwordx4 v[228:231], v[232:233], off offset:16
	s_add_u32 s8, s8, s22
	s_addc_u32 s9, s9, s16
	s_add_i32 s99, s99, 1
